# same as previous but without the static s_setprio 1 for waves 4-7 in the attention phase
# speedup vs baseline: 1.0227x; 1.0013x over previous
; __global__ void __launch_bounds__(NTHR, 2) hybrid_fwd(Args args) {
;     ...
;         PHASE_BEGIN();
;         if (PH(7)) {
;             if (__builtin_amdgcn_readfirstlane(tid) >= 256) __builtin_amdgcn_s_setprio(1);
;             if (G == 256) {
.LBB0_994:
	s_or_b64 exec, exec, s[4:5]
	s_mov_b64 s[4:5], s[86:87]
	s_waitcnt lgkmcnt(0)
	s_barrier
	s_load_dwordx2 s[8:9], s[4:5], 0xf8
	v_mov_b32_e32 v181, v242
	s_mov_b32 s54, s22
	v_readfirstlane_b32 s18, v181
	s_mov_b32 s55, s2
	v_readlane_b32 s4, v255, 8
	s_cmpk_gt_i32 s18, 0xff
	s_cbranch_scc0 .LBB0_996
	s_setprio 0
